# v44: v41 + static priority stagger in the P0 prologue (waves 0-3 at s_setprio 1 from kernel entry; reset at the first GEMM unit header)
# speedup vs baseline: 1.0063x; 1.0006x over previous
_Z6mk_fwd4Args:
	s_load_dword s96, s[0:1], 0x68
	s_add_u32 s4, s0, 0x68
	s_addc_u32 s5, s1, 0
	v_lshl_add_u32 v1, v0, 2, 0
	v_writelane_b32 v251, s4, 0
	v_add_u32_e32 v1, 0x20000, v1
	v_mov_b32_e32 v2, 0
	v_readfirstlane_b32 s44, v0
	v_writelane_b32 v251, s5, 1
	ds_write2st64_b32 v1, v2, v2 offset1:8
	ds_write2st64_b32 v1, v2, v2 offset0:16 offset1:24
	v_or_b32_e32 v1, 0x800, v0
	s_bitcmp1_b32 s44, 8
	s_cbranch_scc1 .Lp0prio_skip
	s_setprio 1
.Lp0prio_skip:
	s_mov_b64 s[4:5], -1
	s_and_saveexec_b64 s[6:7], s[4:5]
	v_lshl_add_u32 v3, v1, 2, 0
	v_add_u32_e32 v3, 0x20000, v3
	ds_write_b32 v3, v2
	s_or_b64 exec, exec, s[6:7]
	s_and_saveexec_b64 s[6:7], s[4:5]
	s_add_i32 s3, 0, 0x20000
	v_lshl_add_u32 v1, v1, 2, s3
	v_mov_b32_e32 v2, 0
	ds_write_b32 v1, v2 offset:2048
	s_or_b64 exec, exec, s[6:7]
	v_or_b32_e32 v1, 0xc00, v0
	v_cmp_gt_u32_e64 s[4:5], 7, 6
	v_cmp_gt_u32_e64 s[8:9], 7, 5
	s_and_saveexec_b64 s[6:7], s[8:9]
	v_lshl_add_u32 v2, v1, 2, 0
	v_add_u32_e32 v2, 0x20000, v2
	v_mov_b32_e32 v3, 0
	ds_write_b32 v2, v3
	s_or_b64 exec, exec, s[6:7]
	s_load_dwordx8 s[88:95], s[0:1], 0x40
	s_and_saveexec_b64 s[6:7], s[4:5]
	s_add_i32 s3, 0, 0x20000
	v_lshl_add_u32 v1, v1, 2, s3
	v_mov_b32_e32 v2, 0
	ds_write_b32 v1, v2 offset:2048
	s_or_b64 exec, exec, s[6:7]
	s_load_dwordx2 s[76:77], s[0:1], 0x60
	s_waitcnt lgkmcnt(0)
	s_barrier
	s_add_u32 s74, s94, 0x4000
	s_getreg_b32 s3, hwreg(HW_REG_XCC_ID, 0, 4)
	s_addc_u32 s75, s95, 0
	s_and_b32 s45, s3, 15
	v_cmp_eq_u32_e64 s[6:7], 0, v0
	s_mov_b64 s[4:5], exec
	s_nop 0
	v_writelane_b32 v251, s6, 2
	s_nop 1
	v_writelane_b32 v251, s7, 3
	s_and_b64 s[6:7], s[4:5], s[6:7]
	s_mov_b64 exec, s[6:7]
	s_cbranch_execz .LBB0_12
	s_mov_b64 s[8:9], exec
	v_mbcnt_lo_u32_b32 v0, s8, 0
	v_mbcnt_hi_u32_b32 v0, s9, v0
	v_cmp_eq_u32_e32 vcc, 0, v0
	s_and_saveexec_b64 s[6:7], vcc
	s_cbranch_execz .LBB0_11
	s_lshl_b32 s3, s45, 8
	s_bcnt1_i32_b64 s8, s[8:9]
	v_mov_b32_e32 v0, s3
	v_mov_b32_e32 v1, s8
	global_atomic_add v0, v1, s[74:75] offset:1024
